# v20: like v19 but the static priority raise is on waves 0-3 (per-half A/B of the raise)
# baseline (speedup 1.0000x reference)
; #define LAS __attribute__((address_space(3)))
; __device__ __forceinline__ void attn_phase_main(const Params& p, LAS unsigned char* lds, int l, int G) {
;     ...
;     volatile LAS float* shl = (volatile LAS float*)(lds + 131072 + 64);
;     __syncthreads();
;     if (tl_ == 0) { shl[0] = shA; shl[1] = shB; shl[2] = shC; shl[3] = shS; shl[4] = shW; }
;     __syncthreads();
;     constexpr int NU = 512 + 512 + 1024;
;     for (int ui = blockIdx.x; ui < NU; ui += G) {
.LBB0_219:
	s_or_b64 exec, exec, s[0:1]
	v_readlane_b32 s0, v250, 27
	v_readlane_b32 s1, v250, 28
	s_andn2_b64 vcc, exec, s[0:1]
	s_waitcnt lgkmcnt(0)
	s_barrier
	s_cbranch_vccnz .LBB0_412
	v_readlane_b32 s0, v254, 23
	v_readlane_b32 s1, v254, 24
	s_lshl_b32 s0, s0, 2
	s_ashr_i32 s1, s0, 31
	v_readlane_b32 s12, v253, 36
	s_lshl_b64 s[0:1], s[0:1], 2
	v_readlane_b32 s16, v253, 40
	v_readlane_b32 s17, v253, 41
	s_add_u32 s0, s16, s0
	s_addc_u32 s1, s17, s1
	v_writelane_b32 v254, s46, 44
	v_writelane_b32 v255, s0, 0
	v_readlane_b32 s13, v253, 37
	v_writelane_b32 v254, s47, 45
	v_writelane_b32 v255, s1, 1
	v_readlane_b32 s0, v250, 0
	s_mov_b32 s96, s0
	v_readlane_b32 s14, v253, 38
	v_readlane_b32 s15, v253, 39
	v_readlane_b32 s18, v253, 42
	v_readlane_b32 s19, v253, 43
	v_readlane_b32 s20, v253, 44
	v_readlane_b32 s21, v253, 45
	v_readlane_b32 s22, v253, 46
	v_readlane_b32 s23, v253, 47
	v_readlane_b32 s24, v253, 48
	v_readlane_b32 s25, v253, 49
	v_readlane_b32 s26, v253, 50
	v_readlane_b32 s27, v253, 51
	v_readfirstlane_b32 vcc_lo, v200
	s_nop 3
	s_lshr_b32 vcc_lo, vcc_lo, 8
	s_cmp_lg_u32 vcc_lo, 0
	s_cbranch_scc1 .Lattn_prio_done
	s_setprio 1
